# GQA loop: row-sum with packed f32 adds over adjacent score registers (17 instead of 32 adds per tile)
# speedup vs baseline: 1.0046x; 1.0046x over previous
; #define MFMA(a, b, c) __builtin_amdgcn_mfma_f32_32x32x16_f16((a), (b), (c), 0, 0, 0)
; template <int DK, bool MLA>
; DI void attn_item(const h16* __restrict__ Q, const h16* __restrict__ Kp, const h16* __restrict__ Kr, const h16* __restrict__ Vt,
;                   int kbeg, int kend, h16* __restrict__ out, h16* sm) {
;     ...
;     float mx = fmaxf(st[0][0], st[1][0]);
; #pragma unroll
;     for (int i = 1; i < 16; ++i) mx = fmaxf(mx, fmaxf(st[0][i], st[1][i]));
;     mx = x32_max(mx);
;     if (__builtin_amdgcn_ballot_w64(mx > 8.f) != 0) {
;       const float dlt = fmaxf(mx, 0.f);
;       const float alpha = __builtin_amdgcn_exp2f(-dlt);
;       m += dlt;
;       lsum *= alpha;
; #pragma unroll
;       for (int i = 0; i < 16; ++i) { ot[0][i] *= alpha; ot[1][i] *= alpha; st[0][i] -= dlt; st[1][i] -= dlt; }
;     }
;     float ps = 0.f;
; #pragma unroll
;     for (int i = 0; i < 16; ++i) {
;       st[0][i] = __builtin_amdgcn_exp2f(st[0][i]);
;       st[1][i] = __builtin_amdgcn_exp2f(st[1][i]);
;       ps += st[0][i] + st[1][i];
;     }
;     lsum += ps;
; #pragma unroll
;     for (int s4 = 0; s4 < 4; ++s4) {
;       const int kt2 = s4 >> 1, hf = s4 & 1;
;       h16x8 pb;
; #pragma unroll
;       for (int j = 0; j < 8; ++j) pb[j] = (h16)st[kt2][8 * hf + j];
;       const int kb = kt2 * 32 + 16 * hf;
; #pragma unroll
;       for (int dt = 0; dt < 2; ++dt) {
;         const h16* vp = vsm + (dt * 32 + r) * 72 + kb + 4 * hh;
;         h16x4 lo = *(const h16x4*)vp, hi = *(const h16x4*)(vp + 8);
;         h16x8 va = __builtin_shufflevector(lo, hi, 0, 1, 2, 3, 4, 5, 6, 7);
;         ot[dt] = MFMA(va, pb, ot[dt]);
;       }
;     }
.Lgq_nl0:
	v_pk_add_f32 v[226:227], v[48:49], v[50:51]
	v_pk_add_f32 v[226:227], v[226:227], v[52:53]
	v_pk_add_f32 v[226:227], v[226:227], v[54:55]
	v_pk_add_f32 v[226:227], v[226:227], v[56:57]
	v_pk_add_f32 v[226:227], v[226:227], v[58:59]
	s_waitcnt lgkmcnt(3)
	v_mfma_f32_32x32x16_f16 v[16:31], v[242:245], v[2:5], v[16:31]
	ds_read_b128 v[242:245], v143 offset:13888
	v_pk_add_f32 v[226:227], v[226:227], v[60:61]
	v_pk_add_f32 v[226:227], v[226:227], v[62:63]
	v_pk_add_f32 v[250:251], v[64:65], v[66:67]
	v_pk_add_f32 v[250:251], v[250:251], v[68:69]
	v_pk_add_f32 v[250:251], v[250:251], v[70:71]
	s_waitcnt lgkmcnt(3)
	v_mfma_f32_32x32x16_f16 v[32:47], v[194:197], v[6:9], v[32:47]
	ds_read_b128 v[194:197], v143 offset:9312
	v_pk_add_f32 v[250:251], v[250:251], v[72:73]
	v_pk_add_f32 v[250:251], v[250:251], v[74:75]
	v_pk_add_f32 v[250:251], v[250:251], v[76:77]
	v_pk_add_f32 v[250:251], v[250:251], v[78:79]
	v_pk_add_f32 v[226:227], v[226:227], v[250:251]
	s_waitcnt lgkmcnt(3)
	v_mfma_f32_32x32x16_f16 v[16:31], v[198:201], v[6:9], v[16:31]
	ds_read_b128 v[198:201], v143 offset:13920
	v_add_f32_e32 v226, v226, v227
	v_add_f32_e32 v153, v153, v226
	v_max3_f32 v0, v162, v163, v164
	v_max3_f32 v14, v165, v166, v167
	v_max3_f32 v15, v168, v169, v170
	s_waitcnt lgkmcnt(3)
	v_mfma_f32_32x32x16_f16 v[32:47], v[238:241], v[10:13], v[32:47]
	v_max3_f32 v202, v171, v172, v173
	v_max3_f32 v0, v0, v174, v175
	v_max3_f32 v14, v14, v176, v177
	v_max3_f32 v15, v15, v178, v179
	v_max3_f32 v202, v202, v180, v181
	s_waitcnt lgkmcnt(2)
	v_mfma_f32_32x32x16_f16 v[16:31], v[242:245], v[10:13], v[16:31]
	v_max3_f32 v0, v0, v182, v183
	v_max3_f32 v14, v14, v184, v185
	v_max3_f32 v15, v15, v186, v187
	v_max3_f32 v202, v202, v188, v189
	s_waitcnt lgkmcnt(1)
	v_mfma_f32_32x32x16_f16 v[32:47], v[194:197], v[246:249], v[32:47]
	v_max3_f32 v0, v0, v190, v191
	v_max3_f32 v14, v14, v192, v193
	v_max3_f32 v0, v0, v14, v15
	v_max_f32_e32 v0, v0, v202
	s_waitcnt lgkmcnt(0)
	v_mfma_f32_32x32x16_f16 v[16:31], v[198:201], v[246:249], v[16:31]
	v_mov_b32_e32 v14, v0
	s_nop 1
	v_permlane32_swap_b32_e32 v0, v14
	v_max_f32_e32 v0, v0, v14
	v_cmp_lt_f32_e32 vcc, s79, v0
	s_cbranch_vccnz .Lgq_rare0

; #define MFMA(a, b, c) __builtin_amdgcn_mfma_f32_32x32x16_f16((a), (b), (c), 0, 0, 0)
; template <int DK, bool MLA>
; DI void attn_item(const h16* __restrict__ Q, const h16* __restrict__ Kp, const h16* __restrict__ Kr, const h16* __restrict__ Vt,
;                   int kbeg, int kend, h16* __restrict__ out, h16* sm) {
;     ...
;     float mx = fmaxf(st[0][0], st[1][0]);
; #pragma unroll
;     for (int i = 1; i < 16; ++i) mx = fmaxf(mx, fmaxf(st[0][i], st[1][i]));
;     mx = x32_max(mx);
;     if (__builtin_amdgcn_ballot_w64(mx > 8.f) != 0) {
;       const float dlt = fmaxf(mx, 0.f);
;       const float alpha = __builtin_amdgcn_exp2f(-dlt);
;       m += dlt;
;       lsum *= alpha;
; #pragma unroll
;       for (int i = 0; i < 16; ++i) { ot[0][i] *= alpha; ot[1][i] *= alpha; st[0][i] -= dlt; st[1][i] -= dlt; }
;     }
;     float ps = 0.f;
; #pragma unroll
;     for (int i = 0; i < 16; ++i) {
;       st[0][i] = __builtin_amdgcn_exp2f(st[0][i]);
;       st[1][i] = __builtin_amdgcn_exp2f(st[1][i]);
;       ps += st[0][i] + st[1][i];
;     }
;     lsum += ps;
; #pragma unroll
;     for (int s4 = 0; s4 < 4; ++s4) {
;       const int kt2 = s4 >> 1, hf = s4 & 1;
;       h16x8 pb;
; #pragma unroll
;       for (int j = 0; j < 8; ++j) pb[j] = (h16)st[kt2][8 * hf + j];
;       const int kb = kt2 * 32 + 16 * hf;
; #pragma unroll
;       for (int dt = 0; dt < 2; ++dt) {
;         const h16* vp = vsm + (dt * 32 + r) * 72 + kb + 4 * hh;
;         h16x4 lo = *(const h16x4*)vp, hi = *(const h16x4*)(vp + 8);
;         h16x8 va = __builtin_shufflevector(lo, hi, 0, 1, 2, 3, 4, 5, 6, 7);
;         ot[dt] = MFMA(va, pb, ot[dt]);
;       }
;     }
.Lgq_nl1:
	v_pk_add_f32 v[226:227], v[162:163], v[164:165]
	v_pk_add_f32 v[226:227], v[226:227], v[166:167]
	v_pk_add_f32 v[226:227], v[226:227], v[168:169]
	v_pk_add_f32 v[226:227], v[226:227], v[170:171]
	v_pk_add_f32 v[226:227], v[226:227], v[172:173]
	s_waitcnt lgkmcnt(3)
	v_mfma_f32_32x32x16_f16 v[16:31], v[242:245], v[2:5], v[16:31]
	ds_read_b128 v[242:245], v143 offset:32320
	v_pk_add_f32 v[226:227], v[226:227], v[174:175]
	v_pk_add_f32 v[226:227], v[226:227], v[176:177]
	v_pk_add_f32 v[250:251], v[178:179], v[180:181]
	v_pk_add_f32 v[250:251], v[250:251], v[182:183]
	v_pk_add_f32 v[250:251], v[250:251], v[184:185]
	s_waitcnt lgkmcnt(3)
	v_mfma_f32_32x32x16_f16 v[32:47], v[194:197], v[6:9], v[32:47]
	ds_read_b128 v[194:197], v143 offset:27744
	v_pk_add_f32 v[250:251], v[250:251], v[186:187]
	v_pk_add_f32 v[250:251], v[250:251], v[188:189]
	v_pk_add_f32 v[250:251], v[250:251], v[190:191]
	v_pk_add_f32 v[250:251], v[250:251], v[192:193]
	v_pk_add_f32 v[226:227], v[226:227], v[250:251]
	s_waitcnt lgkmcnt(3)
	v_mfma_f32_32x32x16_f16 v[16:31], v[198:201], v[6:9], v[16:31]
	ds_read_b128 v[198:201], v143 offset:32352
	v_add_f32_e32 v226, v226, v227
	v_add_f32_e32 v153, v153, v226
	v_max3_f32 v0, v48, v49, v50
	v_max3_f32 v14, v51, v52, v53
	v_max3_f32 v15, v54, v55, v56
	s_waitcnt lgkmcnt(3)
	v_mfma_f32_32x32x16_f16 v[32:47], v[238:241], v[10:13], v[32:47]
	v_max3_f32 v202, v57, v58, v59
	v_max3_f32 v0, v0, v60, v61
	v_max3_f32 v14, v14, v62, v63
	v_max3_f32 v15, v15, v64, v65
	v_max3_f32 v202, v202, v66, v67
	s_waitcnt lgkmcnt(2)
	v_mfma_f32_32x32x16_f16 v[16:31], v[242:245], v[10:13], v[16:31]
	v_max3_f32 v0, v0, v68, v69
	v_max3_f32 v14, v14, v70, v71
	v_max3_f32 v15, v15, v72, v73
	v_max3_f32 v202, v202, v74, v75
	s_waitcnt lgkmcnt(1)
	v_mfma_f32_32x32x16_f16 v[32:47], v[194:197], v[246:249], v[32:47]
	v_max3_f32 v0, v0, v76, v77
	v_max3_f32 v14, v14, v78, v79
	v_max3_f32 v0, v0, v14, v15
	v_max_f32_e32 v0, v0, v202
	s_waitcnt lgkmcnt(0)
	v_mfma_f32_32x32x16_f16 v[16:31], v[198:201], v[246:249], v[16:31]
	v_mov_b32_e32 v14, v0
	s_nop 1
	v_permlane32_swap_b32_e32 v0, v14
	v_max_f32_e32 v0, v0, v14
	v_cmp_lt_f32_e32 vcc, s79, v0
	s_cbranch_vccnz .Lgq_rare1

; #define MFMA(a, b, c) __builtin_amdgcn_mfma_f32_32x32x16_f16((a), (b), (c), 0, 0, 0)
; template <int DK, bool MLA>
; DI void attn_item(const h16* __restrict__ Q, const h16* __restrict__ Kp, const h16* __restrict__ Kr, const h16* __restrict__ Vt,
;                   int kbeg, int kend, h16* __restrict__ out, h16* sm) {
;     ...
;     float mx = fmaxf(st[0][0], st[1][0]);
; #pragma unroll
;     for (int i = 1; i < 16; ++i) mx = fmaxf(mx, fmaxf(st[0][i], st[1][i]));
;     mx = x32_max(mx);
;     if (__builtin_amdgcn_ballot_w64(mx > 8.f) != 0) {
;       const float dlt = fmaxf(mx, 0.f);
;       const float alpha = __builtin_amdgcn_exp2f(-dlt);
;       m += dlt;
;       lsum *= alpha;
; #pragma unroll
;       for (int i = 0; i < 16; ++i) { ot[0][i] *= alpha; ot[1][i] *= alpha; st[0][i] -= dlt; st[1][i] -= dlt; }
;     }
;     float ps = 0.f;
; #pragma unroll
;     for (int i = 0; i < 16; ++i) {
;       st[0][i] = __builtin_amdgcn_exp2f(st[0][i]);
;       st[1][i] = __builtin_amdgcn_exp2f(st[1][i]);
;       ps += st[0][i] + st[1][i];
;     }
;     lsum += ps;
; #pragma unroll
;     for (int s4 = 0; s4 < 4; ++s4) {
;       const int kt2 = s4 >> 1, hf = s4 & 1;
;       h16x8 pb;
; #pragma unroll
;       for (int j = 0; j < 8; ++j) pb[j] = (h16)st[kt2][8 * hf + j];
;       const int kb = kt2 * 32 + 16 * hf;
; #pragma unroll
;       for (int dt = 0; dt < 2; ++dt) {
;         const h16* vp = vsm + (dt * 32 + r) * 72 + kb + 4 * hh;
;         h16x4 lo = *(const h16x4*)vp, hi = *(const h16x4*)(vp + 8);
;         h16x8 va = __builtin_shufflevector(lo, hi, 0, 1, 2, 3, 4, 5, 6, 7);
;         ot[dt] = MFMA(va, pb, ot[dt]);
;       }
;     }
.Lgq_nl2:
	v_pk_add_f32 v[226:227], v[48:49], v[50:51]
	v_pk_add_f32 v[226:227], v[226:227], v[52:53]
	v_pk_add_f32 v[226:227], v[226:227], v[54:55]
	v_pk_add_f32 v[226:227], v[226:227], v[56:57]
	v_pk_add_f32 v[226:227], v[226:227], v[58:59]
	s_waitcnt lgkmcnt(3)
	v_mfma_f32_32x32x16_f16 v[16:31], v[242:245], v[2:5], v[16:31]
	ds_read_b128 v[242:245], v143 offset:50752
	v_pk_add_f32 v[226:227], v[226:227], v[60:61]
	v_pk_add_f32 v[226:227], v[226:227], v[62:63]
	v_pk_add_f32 v[250:251], v[64:65], v[66:67]
	v_pk_add_f32 v[250:251], v[250:251], v[68:69]
	v_pk_add_f32 v[250:251], v[250:251], v[70:71]
	s_waitcnt lgkmcnt(3)
	v_mfma_f32_32x32x16_f16 v[32:47], v[194:197], v[6:9], v[32:47]
	ds_read_b128 v[194:197], v143 offset:46176
	v_pk_add_f32 v[250:251], v[250:251], v[72:73]
	v_pk_add_f32 v[250:251], v[250:251], v[74:75]
	v_pk_add_f32 v[250:251], v[250:251], v[76:77]
	v_pk_add_f32 v[250:251], v[250:251], v[78:79]
	v_pk_add_f32 v[226:227], v[226:227], v[250:251]
	s_waitcnt lgkmcnt(3)
	v_mfma_f32_32x32x16_f16 v[16:31], v[198:201], v[6:9], v[16:31]
	ds_read_b128 v[198:201], v143 offset:50784
	v_add_f32_e32 v226, v226, v227
	v_add_f32_e32 v153, v153, v226
	v_max3_f32 v0, v162, v163, v164
	v_max3_f32 v14, v165, v166, v167
	v_max3_f32 v15, v168, v169, v170
	s_waitcnt lgkmcnt(3)
	v_mfma_f32_32x32x16_f16 v[32:47], v[238:241], v[10:13], v[32:47]
	v_max3_f32 v202, v171, v172, v173
	v_max3_f32 v0, v0, v174, v175
	v_max3_f32 v14, v14, v176, v177
	v_max3_f32 v15, v15, v178, v179
	v_max3_f32 v202, v202, v180, v181
	s_waitcnt lgkmcnt(2)
	v_mfma_f32_32x32x16_f16 v[16:31], v[242:245], v[10:13], v[16:31]
	v_max3_f32 v0, v0, v182, v183
	v_max3_f32 v14, v14, v184, v185
	v_max3_f32 v15, v15, v186, v187
	v_max3_f32 v202, v202, v188, v189
	s_waitcnt lgkmcnt(1)
	v_mfma_f32_32x32x16_f16 v[32:47], v[194:197], v[246:249], v[32:47]
	v_max3_f32 v0, v0, v190, v191
	v_max3_f32 v14, v14, v192, v193
	v_max3_f32 v0, v0, v14, v15
	v_max_f32_e32 v0, v0, v202
	s_waitcnt lgkmcnt(0)
	v_mfma_f32_32x32x16_f16 v[16:31], v[198:201], v[246:249], v[16:31]
	v_mov_b32_e32 v14, v0
	s_nop 1
	v_permlane32_swap_b32_e32 v0, v14
	v_max_f32_e32 v0, v0, v14
	v_cmp_lt_f32_e32 vcc, s79, v0
	s_cbranch_vccnz .Lgq_rare2

; #define MFMA(a, b, c) __builtin_amdgcn_mfma_f32_32x32x16_f16((a), (b), (c), 0, 0, 0)
; template <int DK, bool MLA>
; DI void attn_item(const h16* __restrict__ Q, const h16* __restrict__ Kp, const h16* __restrict__ Kr, const h16* __restrict__ Vt,
;                   int kbeg, int kend, h16* __restrict__ out, h16* sm) {
;     ...
;     float mx = fmaxf(st[0][0], st[1][0]);
; #pragma unroll
;     for (int i = 1; i < 16; ++i) mx = fmaxf(mx, fmaxf(st[0][i], st[1][i]));
;     mx = x32_max(mx);
;     if (__builtin_amdgcn_ballot_w64(mx > 8.f) != 0) {
;       const float dlt = fmaxf(mx, 0.f);
;       const float alpha = __builtin_amdgcn_exp2f(-dlt);
;       m += dlt;
;       lsum *= alpha;
; #pragma unroll
;       for (int i = 0; i < 16; ++i) { ot[0][i] *= alpha; ot[1][i] *= alpha; st[0][i] -= dlt; st[1][i] -= dlt; }
;     }
;     float ps = 0.f;
; #pragma unroll
;     for (int i = 0; i < 16; ++i) {
;       st[0][i] = __builtin_amdgcn_exp2f(st[0][i]);
;       st[1][i] = __builtin_amdgcn_exp2f(st[1][i]);
;       ps += st[0][i] + st[1][i];
;     }
;     lsum += ps;
; #pragma unroll
;     for (int s4 = 0; s4 < 4; ++s4) {
;       const int kt2 = s4 >> 1, hf = s4 & 1;
;       h16x8 pb;
; #pragma unroll
;       for (int j = 0; j < 8; ++j) pb[j] = (h16)st[kt2][8 * hf + j];
;       const int kb = kt2 * 32 + 16 * hf;
; #pragma unroll
;       for (int dt = 0; dt < 2; ++dt) {
;         const h16* vp = vsm + (dt * 32 + r) * 72 + kb + 4 * hh;
;         h16x4 lo = *(const h16x4*)vp, hi = *(const h16x4*)(vp + 8);
;         h16x8 va = __builtin_shufflevector(lo, hi, 0, 1, 2, 3, 4, 5, 6, 7);
;         ot[dt] = MFMA(va, pb, ot[dt]);
;       }
;     }
.Lgq_nl3:
	v_pk_add_f32 v[226:227], v[162:163], v[164:165]
	v_pk_add_f32 v[226:227], v[226:227], v[166:167]
	v_pk_add_f32 v[226:227], v[226:227], v[168:169]
	v_pk_add_f32 v[226:227], v[226:227], v[170:171]
	v_pk_add_f32 v[226:227], v[226:227], v[172:173]
	s_waitcnt lgkmcnt(3)
	v_mfma_f32_32x32x16_f16 v[16:31], v[242:245], v[2:5], v[16:31]
	ds_read_b128 v[242:245], v143 offset:13888
	v_pk_add_f32 v[226:227], v[226:227], v[174:175]
	v_pk_add_f32 v[226:227], v[226:227], v[176:177]
	v_pk_add_f32 v[250:251], v[178:179], v[180:181]
	v_pk_add_f32 v[250:251], v[250:251], v[182:183]
	v_pk_add_f32 v[250:251], v[250:251], v[184:185]
	s_waitcnt lgkmcnt(3)
	v_mfma_f32_32x32x16_f16 v[32:47], v[194:197], v[6:9], v[32:47]
	ds_read_b128 v[194:197], v143 offset:9312
	v_pk_add_f32 v[250:251], v[250:251], v[186:187]
	v_pk_add_f32 v[250:251], v[250:251], v[188:189]
	v_pk_add_f32 v[250:251], v[250:251], v[190:191]
	v_pk_add_f32 v[250:251], v[250:251], v[192:193]
	v_pk_add_f32 v[226:227], v[226:227], v[250:251]
	s_waitcnt lgkmcnt(3)
	v_mfma_f32_32x32x16_f16 v[16:31], v[198:201], v[6:9], v[16:31]
	ds_read_b128 v[198:201], v143 offset:13920
	v_add_f32_e32 v226, v226, v227
	v_add_f32_e32 v153, v153, v226
	v_max3_f32 v0, v48, v49, v50
	v_max3_f32 v14, v51, v52, v53
	v_max3_f32 v15, v54, v55, v56
	s_waitcnt lgkmcnt(3)
	v_mfma_f32_32x32x16_f16 v[32:47], v[238:241], v[10:13], v[32:47]
	v_max3_f32 v202, v57, v58, v59
	v_max3_f32 v0, v0, v60, v61
	v_max3_f32 v14, v14, v62, v63
	v_max3_f32 v15, v15, v64, v65
	v_max3_f32 v202, v202, v66, v67
	s_waitcnt lgkmcnt(2)
	v_mfma_f32_32x32x16_f16 v[16:31], v[242:245], v[10:13], v[16:31]
	v_max3_f32 v0, v0, v68, v69
	v_max3_f32 v14, v14, v70, v71
	v_max3_f32 v15, v15, v72, v73
	v_max3_f32 v202, v202, v74, v75
	s_waitcnt lgkmcnt(1)
	v_mfma_f32_32x32x16_f16 v[32:47], v[194:197], v[246:249], v[32:47]
	v_max3_f32 v0, v0, v76, v77
	v_max3_f32 v14, v14, v78, v79
	v_max3_f32 v0, v0, v14, v15
	v_max_f32_e32 v0, v0, v202
	s_waitcnt lgkmcnt(0)
	v_mfma_f32_32x32x16_f16 v[16:31], v[198:201], v[246:249], v[16:31]
	v_mov_b32_e32 v14, v0
	s_nop 1
	v_permlane32_swap_b32_e32 v0, v14
	v_max_f32_e32 v0, v0, v14
	v_cmp_lt_f32_e32 vcc, s79, v0
	s_cbranch_vccnz .Lgq_rare3

; #define MFMA(a, b, c) __builtin_amdgcn_mfma_f32_32x32x16_f16((a), (b), (c), 0, 0, 0)
; template <int DK, bool MLA>
; DI void attn_item(const h16* __restrict__ Q, const h16* __restrict__ Kp, const h16* __restrict__ Kr, const h16* __restrict__ Vt,
;                   int kbeg, int kend, h16* __restrict__ out, h16* sm) {
;     ...
;     float mx = fmaxf(st[0][0], st[1][0]);
; #pragma unroll
;     for (int i = 1; i < 16; ++i) mx = fmaxf(mx, fmaxf(st[0][i], st[1][i]));
;     mx = x32_max(mx);
;     if (__builtin_amdgcn_ballot_w64(mx > 8.f) != 0) {
;       const float dlt = fmaxf(mx, 0.f);
;       const float alpha = __builtin_amdgcn_exp2f(-dlt);
;       m += dlt;
;       lsum *= alpha;
; #pragma unroll
;       for (int i = 0; i < 16; ++i) { ot[0][i] *= alpha; ot[1][i] *= alpha; st[0][i] -= dlt; st[1][i] -= dlt; }
;     }
;     float ps = 0.f;
; #pragma unroll
;     for (int i = 0; i < 16; ++i) {
;       st[0][i] = __builtin_amdgcn_exp2f(st[0][i]);
;       st[1][i] = __builtin_amdgcn_exp2f(st[1][i]);
;       ps += st[0][i] + st[1][i];
;     }
;     lsum += ps;
; #pragma unroll
;     for (int s4 = 0; s4 < 4; ++s4) {
;       const int kt2 = s4 >> 1, hf = s4 & 1;
;       h16x8 pb;
; #pragma unroll
;       for (int j = 0; j < 8; ++j) pb[j] = (h16)st[kt2][8 * hf + j];
;       const int kb = kt2 * 32 + 16 * hf;
; #pragma unroll
;       for (int dt = 0; dt < 2; ++dt) {
;         const h16* vp = vsm + (dt * 32 + r) * 72 + kb + 4 * hh;
;         h16x4 lo = *(const h16x4*)vp, hi = *(const h16x4*)(vp + 8);
;         h16x8 va = __builtin_shufflevector(lo, hi, 0, 1, 2, 3, 4, 5, 6, 7);
;         ot[dt] = MFMA(va, pb, ot[dt]);
;       }
;     }
.Lgq_nl4:
	v_pk_add_f32 v[226:227], v[48:49], v[50:51]
	v_pk_add_f32 v[226:227], v[226:227], v[52:53]
	v_pk_add_f32 v[226:227], v[226:227], v[54:55]
	v_pk_add_f32 v[226:227], v[226:227], v[56:57]
	v_pk_add_f32 v[226:227], v[226:227], v[58:59]
	s_waitcnt lgkmcnt(3)
	v_mfma_f32_32x32x16_f16 v[16:31], v[242:245], v[2:5], v[16:31]
	ds_read_b128 v[242:245], v143 offset:32320
	v_pk_add_f32 v[226:227], v[226:227], v[60:61]
	v_pk_add_f32 v[226:227], v[226:227], v[62:63]
	v_pk_add_f32 v[250:251], v[64:65], v[66:67]
	v_pk_add_f32 v[250:251], v[250:251], v[68:69]
	v_pk_add_f32 v[250:251], v[250:251], v[70:71]
	s_waitcnt lgkmcnt(3)
	v_mfma_f32_32x32x16_f16 v[32:47], v[194:197], v[6:9], v[32:47]
	ds_read_b128 v[194:197], v143 offset:27744
	v_pk_add_f32 v[250:251], v[250:251], v[72:73]
	v_pk_add_f32 v[250:251], v[250:251], v[74:75]
	v_pk_add_f32 v[250:251], v[250:251], v[76:77]
	v_pk_add_f32 v[250:251], v[250:251], v[78:79]
	v_pk_add_f32 v[226:227], v[226:227], v[250:251]
	s_waitcnt lgkmcnt(3)
	v_mfma_f32_32x32x16_f16 v[16:31], v[198:201], v[6:9], v[16:31]
	ds_read_b128 v[198:201], v143 offset:32352
	v_add_f32_e32 v226, v226, v227
	v_add_f32_e32 v153, v153, v226
	v_max3_f32 v0, v162, v163, v164
	v_max3_f32 v14, v165, v166, v167
	v_max3_f32 v15, v168, v169, v170
	s_waitcnt lgkmcnt(3)
	v_mfma_f32_32x32x16_f16 v[32:47], v[238:241], v[10:13], v[32:47]
	v_max3_f32 v202, v171, v172, v173
	v_max3_f32 v0, v0, v174, v175
	v_max3_f32 v14, v14, v176, v177
	v_max3_f32 v15, v15, v178, v179
	v_max3_f32 v202, v202, v180, v181
	s_waitcnt lgkmcnt(2)
	v_mfma_f32_32x32x16_f16 v[16:31], v[242:245], v[10:13], v[16:31]
	v_max3_f32 v0, v0, v182, v183
	v_max3_f32 v14, v14, v184, v185
	v_max3_f32 v15, v15, v186, v187
	v_max3_f32 v202, v202, v188, v189
	s_waitcnt lgkmcnt(1)
	v_mfma_f32_32x32x16_f16 v[32:47], v[194:197], v[246:249], v[32:47]
	v_max3_f32 v0, v0, v190, v191
	v_max3_f32 v14, v14, v192, v193
	v_max3_f32 v0, v0, v14, v15
	v_max_f32_e32 v0, v0, v202
	s_waitcnt lgkmcnt(0)
	v_mfma_f32_32x32x16_f16 v[16:31], v[198:201], v[246:249], v[16:31]
	v_mov_b32_e32 v14, v0
	s_nop 1
	v_permlane32_swap_b32_e32 v0, v14
	v_max_f32_e32 v0, v0, v14
	v_cmp_lt_f32_e32 vcc, s79, v0
	s_cbranch_vccnz .Lgq_rare4

; #define MFMA(a, b, c) __builtin_amdgcn_mfma_f32_32x32x16_f16((a), (b), (c), 0, 0, 0)
; template <int DK, bool MLA>
; DI void attn_item(const h16* __restrict__ Q, const h16* __restrict__ Kp, const h16* __restrict__ Kr, const h16* __restrict__ Vt,
;                   int kbeg, int kend, h16* __restrict__ out, h16* sm) {
;     ...
;     float mx = fmaxf(st[0][0], st[1][0]);
; #pragma unroll
;     for (int i = 1; i < 16; ++i) mx = fmaxf(mx, fmaxf(st[0][i], st[1][i]));
;     mx = x32_max(mx);
;     if (__builtin_amdgcn_ballot_w64(mx > 8.f) != 0) {
;       const float dlt = fmaxf(mx, 0.f);
;       const float alpha = __builtin_amdgcn_exp2f(-dlt);
;       m += dlt;
;       lsum *= alpha;
; #pragma unroll
;       for (int i = 0; i < 16; ++i) { ot[0][i] *= alpha; ot[1][i] *= alpha; st[0][i] -= dlt; st[1][i] -= dlt; }
;     }
;     float ps = 0.f;
; #pragma unroll
;     for (int i = 0; i < 16; ++i) {
;       st[0][i] = __builtin_amdgcn_exp2f(st[0][i]);
;       st[1][i] = __builtin_amdgcn_exp2f(st[1][i]);
;       ps += st[0][i] + st[1][i];
;     }
;     lsum += ps;
; #pragma unroll
;     for (int s4 = 0; s4 < 4; ++s4) {
;       const int kt2 = s4 >> 1, hf = s4 & 1;
;       h16x8 pb;
; #pragma unroll
;       for (int j = 0; j < 8; ++j) pb[j] = (h16)st[kt2][8 * hf + j];
;       const int kb = kt2 * 32 + 16 * hf;
; #pragma unroll
;       for (int dt = 0; dt < 2; ++dt) {
;         const h16* vp = vsm + (dt * 32 + r) * 72 + kb + 4 * hh;
;         h16x4 lo = *(const h16x4*)vp, hi = *(const h16x4*)(vp + 8);
;         h16x8 va = __builtin_shufflevector(lo, hi, 0, 1, 2, 3, 4, 5, 6, 7);
;         ot[dt] = MFMA(va, pb, ot[dt]);
;       }
;     }
.Lgq_nl5:
	v_pk_add_f32 v[226:227], v[162:163], v[164:165]
	v_pk_add_f32 v[226:227], v[226:227], v[166:167]
	v_pk_add_f32 v[226:227], v[226:227], v[168:169]
	v_pk_add_f32 v[226:227], v[226:227], v[170:171]
	v_pk_add_f32 v[226:227], v[226:227], v[172:173]
	s_waitcnt lgkmcnt(3)
	v_mfma_f32_32x32x16_f16 v[16:31], v[242:245], v[2:5], v[16:31]
	ds_read_b128 v[242:245], v143 offset:50752
	v_pk_add_f32 v[226:227], v[226:227], v[174:175]
	v_pk_add_f32 v[226:227], v[226:227], v[176:177]
	v_pk_add_f32 v[250:251], v[178:179], v[180:181]
	v_pk_add_f32 v[250:251], v[250:251], v[182:183]
	v_pk_add_f32 v[250:251], v[250:251], v[184:185]
	s_waitcnt lgkmcnt(3)
	v_mfma_f32_32x32x16_f16 v[32:47], v[194:197], v[6:9], v[32:47]
	ds_read_b128 v[194:197], v143 offset:46176
	v_pk_add_f32 v[250:251], v[250:251], v[186:187]
	v_pk_add_f32 v[250:251], v[250:251], v[188:189]
	v_pk_add_f32 v[250:251], v[250:251], v[190:191]
	v_pk_add_f32 v[250:251], v[250:251], v[192:193]
	v_pk_add_f32 v[226:227], v[226:227], v[250:251]
	s_waitcnt lgkmcnt(3)
	v_mfma_f32_32x32x16_f16 v[16:31], v[198:201], v[6:9], v[16:31]
	ds_read_b128 v[198:201], v143 offset:50784
	v_add_f32_e32 v226, v226, v227
	v_add_f32_e32 v153, v153, v226
	v_max3_f32 v0, v48, v49, v50
	v_max3_f32 v14, v51, v52, v53
	v_max3_f32 v15, v54, v55, v56
	s_waitcnt lgkmcnt(3)
	v_mfma_f32_32x32x16_f16 v[32:47], v[238:241], v[10:13], v[32:47]
	v_max3_f32 v202, v57, v58, v59
	v_max3_f32 v0, v0, v60, v61
	v_max3_f32 v14, v14, v62, v63
	v_max3_f32 v15, v15, v64, v65
	v_max3_f32 v202, v202, v66, v67
	s_waitcnt lgkmcnt(2)
	v_mfma_f32_32x32x16_f16 v[16:31], v[242:245], v[10:13], v[16:31]
	v_max3_f32 v0, v0, v68, v69
	v_max3_f32 v14, v14, v70, v71
	v_max3_f32 v15, v15, v72, v73
	v_max3_f32 v202, v202, v74, v75
	s_waitcnt lgkmcnt(1)
	v_mfma_f32_32x32x16_f16 v[32:47], v[194:197], v[246:249], v[32:47]
	v_max3_f32 v0, v0, v76, v77
	v_max3_f32 v14, v14, v78, v79
	v_max3_f32 v0, v0, v14, v15
	v_max_f32_e32 v0, v0, v202
	s_waitcnt lgkmcnt(0)
	v_mfma_f32_32x32x16_f16 v[16:31], v[198:201], v[246:249], v[16:31]
	v_mov_b32_e32 v14, v0
	s_nop 1
	v_permlane32_swap_b32_e32 v0, v14
	v_max_f32_e32 v0, v0, v14
	v_cmp_lt_f32_e32 vcc, s79, v0
	s_cbranch_vccnz .Lgq_rare5

; #define MFMA(a, b, c) __builtin_amdgcn_mfma_f32_32x32x16_f16((a), (b), (c), 0, 0, 0)
; template <int DK, bool MLA>
; DI void attn_item(const h16* __restrict__ Q, const h16* __restrict__ Kp, const h16* __restrict__ Kr, const h16* __restrict__ Vt,
;                   int kbeg, int kend, h16* __restrict__ out, h16* sm) {
;     ...
;     float ps = 0.f;
; #pragma unroll
;     for (int i = 0; i < 16; ++i) {
;       st[0][i] = __builtin_amdgcn_exp2f(st[0][i]);
;       st[1][i] = __builtin_amdgcn_exp2f(st[1][i]);
;       ps += st[0][i] + st[1][i];
;     }
;     lsum += ps;
; #pragma unroll
;     for (int s4 = 0; s4 < 4; ++s4) {
;       const int kt2 = s4 >> 1, hf = s4 & 1;
;       h16x8 pb;
; #pragma unroll
;       for (int j = 0; j < 8; ++j) pb[j] = (h16)st[kt2][8 * hf + j];
;       const int kb = kt2 * 32 + 16 * hf;
; #pragma unroll
;       for (int dt = 0; dt < 2; ++dt) {
;         const h16* vp = vsm + (dt * 32 + r) * 72 + kb + 4 * hh;
;         h16x4 lo = *(const h16x4*)vp, hi = *(const h16x4*)(vp + 8);
;         h16x8 va = __builtin_shufflevector(lo, hi, 0, 1, 2, 3, 4, 5, 6, 7);
;         ot[dt] = MFMA(va, pb, ot[dt]);
;       }
;     }
.Lgq_drain0:
	ds_read_b128 v[238:241], v143 offset:9216
	ds_read_b128 v[242:245], v143 offset:13824
	ds_read_b128 v[194:197], v143 offset:9248
	ds_read_b128 v[198:201], v143 offset:13856
	v_exp_f32_e32 v162, v162
	v_exp_f32_e32 v163, v163
	v_exp_f32_e32 v164, v164
	v_exp_f32_e32 v165, v165
	v_exp_f32_e32 v166, v166
	v_exp_f32_e32 v167, v167
	v_exp_f32_e32 v168, v168
	v_exp_f32_e32 v169, v169
	v_cvt_pk_f16_f32 v2, v162, v163
	v_cvt_pk_f16_f32 v3, v164, v165
	v_exp_f32_e32 v170, v170
	v_exp_f32_e32 v171, v171
	v_exp_f32_e32 v172, v172
	v_exp_f32_e32 v173, v173
	v_cvt_pk_f16_f32 v4, v166, v167
	v_cvt_pk_f16_f32 v5, v168, v169
	v_exp_f32_e32 v174, v174
	v_exp_f32_e32 v175, v175
	v_exp_f32_e32 v176, v176
	v_exp_f32_e32 v177, v177
	v_cvt_pk_f16_f32 v6, v170, v171
	v_cvt_pk_f16_f32 v7, v172, v173
	v_exp_f32_e32 v178, v178
	v_exp_f32_e32 v179, v179
	v_exp_f32_e32 v180, v180
	v_exp_f32_e32 v181, v181
	v_cvt_pk_f16_f32 v8, v174, v175
	v_cvt_pk_f16_f32 v9, v176, v177
	v_exp_f32_e32 v182, v182
	v_exp_f32_e32 v183, v183
	v_exp_f32_e32 v184, v184
	v_exp_f32_e32 v185, v185
	v_cvt_pk_f16_f32 v10, v178, v179
	v_cvt_pk_f16_f32 v11, v180, v181
	v_exp_f32_e32 v186, v186
	v_exp_f32_e32 v187, v187
	v_exp_f32_e32 v188, v188
	v_exp_f32_e32 v189, v189
	v_cvt_pk_f16_f32 v12, v182, v183
	v_cvt_pk_f16_f32 v13, v184, v185
	v_exp_f32_e32 v190, v190
	v_exp_f32_e32 v191, v191
	v_exp_f32_e32 v192, v192
	v_exp_f32_e32 v193, v193
	v_cvt_pk_f16_f32 v246, v186, v187
	v_cvt_pk_f16_f32 v247, v188, v189
	v_cvt_pk_f16_f32 v248, v190, v191
	v_cvt_pk_f16_f32 v249, v192, v193
	s_nop 1
	s_waitcnt lgkmcnt(3)
	v_mfma_f32_32x32x16_f16 v[32:47], v[238:241], v[2:5], v[32:47]
	ds_read_b128 v[238:241], v143 offset:9280
	v_pk_add_f32 v[226:227], v[162:163], v[164:165]
	v_pk_add_f32 v[226:227], v[226:227], v[166:167]
	v_pk_add_f32 v[226:227], v[226:227], v[168:169]
	s_waitcnt lgkmcnt(3)
	v_mfma_f32_32x32x16_f16 v[16:31], v[242:245], v[2:5], v[16:31]
	ds_read_b128 v[242:245], v143 offset:13888
	v_pk_add_f32 v[226:227], v[226:227], v[170:171]
	v_pk_add_f32 v[226:227], v[226:227], v[172:173]
	v_pk_add_f32 v[226:227], v[226:227], v[174:175]
	s_waitcnt lgkmcnt(3)
	v_mfma_f32_32x32x16_f16 v[32:47], v[194:197], v[6:9], v[32:47]
	ds_read_b128 v[194:197], v143 offset:9312
	v_pk_add_f32 v[226:227], v[226:227], v[176:177]
	v_pk_add_f32 v[250:251], v[178:179], v[180:181]
	v_pk_add_f32 v[250:251], v[250:251], v[182:183]
	s_waitcnt lgkmcnt(3)
	v_mfma_f32_32x32x16_f16 v[16:31], v[198:201], v[6:9], v[16:31]
	ds_read_b128 v[198:201], v143 offset:13920
	v_pk_add_f32 v[250:251], v[250:251], v[184:185]
	v_pk_add_f32 v[250:251], v[250:251], v[186:187]
	v_pk_add_f32 v[250:251], v[250:251], v[188:189]
	s_waitcnt lgkmcnt(3)
	v_mfma_f32_32x32x16_f16 v[32:47], v[238:241], v[10:13], v[32:47]
	v_pk_add_f32 v[250:251], v[250:251], v[190:191]
	v_pk_add_f32 v[250:251], v[250:251], v[192:193]
	v_pk_add_f32 v[226:227], v[226:227], v[250:251]
	s_waitcnt lgkmcnt(2)
	v_mfma_f32_32x32x16_f16 v[16:31], v[242:245], v[10:13], v[16:31]
	v_add_f32_e32 v226, v226, v227
	v_add_f32_e32 v153, v153, v226
	s_waitcnt lgkmcnt(1)
	v_mfma_f32_32x32x16_f16 v[32:47], v[194:197], v[246:249], v[32:47]
	s_waitcnt lgkmcnt(0)
	v_mfma_f32_32x32x16_f16 v[16:31], v[198:201], v[246:249], v[16:31]
	s_branch .LBB0_2743
.Lgq_drain1:
	ds_read_b128 v[238:241], v143 offset:27648
	ds_read_b128 v[242:245], v143 offset:32256
	ds_read_b128 v[194:197], v143 offset:27680
	ds_read_b128 v[198:201], v143 offset:32288
	v_exp_f32_e32 v162, v162
	v_exp_f32_e32 v163, v163
	v_exp_f32_e32 v164, v164
	v_exp_f32_e32 v165, v165
	v_exp_f32_e32 v166, v166
	v_exp_f32_e32 v167, v167
	v_exp_f32_e32 v168, v168
	v_exp_f32_e32 v169, v169
	v_cvt_pk_f16_f32 v2, v162, v163
	v_cvt_pk_f16_f32 v3, v164, v165
	v_exp_f32_e32 v170, v170
	v_exp_f32_e32 v171, v171
	v_exp_f32_e32 v172, v172
	v_exp_f32_e32 v173, v173
	v_cvt_pk_f16_f32 v4, v166, v167
	v_cvt_pk_f16_f32 v5, v168, v169
	v_exp_f32_e32 v174, v174
	v_exp_f32_e32 v175, v175
	v_exp_f32_e32 v176, v176
	v_exp_f32_e32 v177, v177
	v_cvt_pk_f16_f32 v6, v170, v171
	v_cvt_pk_f16_f32 v7, v172, v173
	v_exp_f32_e32 v178, v178
	v_exp_f32_e32 v179, v179
	v_exp_f32_e32 v180, v180
	v_exp_f32_e32 v181, v181
	v_cvt_pk_f16_f32 v8, v174, v175
	v_cvt_pk_f16_f32 v9, v176, v177
	v_exp_f32_e32 v182, v182
	v_exp_f32_e32 v183, v183
	v_exp_f32_e32 v184, v184
	v_exp_f32_e32 v185, v185
	v_cvt_pk_f16_f32 v10, v178, v179
	v_cvt_pk_f16_f32 v11, v180, v181
	v_exp_f32_e32 v186, v186
	v_exp_f32_e32 v187, v187
	v_exp_f32_e32 v188, v188
	v_exp_f32_e32 v189, v189
	v_cvt_pk_f16_f32 v12, v182, v183
	v_cvt_pk_f16_f32 v13, v184, v185
	v_exp_f32_e32 v190, v190
	v_exp_f32_e32 v191, v191
	v_exp_f32_e32 v192, v192
	v_exp_f32_e32 v193, v193
	v_cvt_pk_f16_f32 v246, v186, v187
	v_cvt_pk_f16_f32 v247, v188, v189
	v_cvt_pk_f16_f32 v248, v190, v191
	v_cvt_pk_f16_f32 v249, v192, v193
	s_nop 1
	s_waitcnt lgkmcnt(3)
	v_mfma_f32_32x32x16_f16 v[32:47], v[238:241], v[2:5], v[32:47]
	ds_read_b128 v[238:241], v143 offset:27712
	v_pk_add_f32 v[226:227], v[162:163], v[164:165]
	v_pk_add_f32 v[226:227], v[226:227], v[166:167]
	v_pk_add_f32 v[226:227], v[226:227], v[168:169]
	s_waitcnt lgkmcnt(3)
	v_mfma_f32_32x32x16_f16 v[16:31], v[242:245], v[2:5], v[16:31]
	ds_read_b128 v[242:245], v143 offset:32320
	v_pk_add_f32 v[226:227], v[226:227], v[170:171]
	v_pk_add_f32 v[226:227], v[226:227], v[172:173]
	v_pk_add_f32 v[226:227], v[226:227], v[174:175]
	s_waitcnt lgkmcnt(3)
	v_mfma_f32_32x32x16_f16 v[32:47], v[194:197], v[6:9], v[32:47]
	ds_read_b128 v[194:197], v143 offset:27744
	v_pk_add_f32 v[226:227], v[226:227], v[176:177]
	v_pk_add_f32 v[250:251], v[178:179], v[180:181]
	v_pk_add_f32 v[250:251], v[250:251], v[182:183]
	s_waitcnt lgkmcnt(3)
	v_mfma_f32_32x32x16_f16 v[16:31], v[198:201], v[6:9], v[16:31]
	ds_read_b128 v[198:201], v143 offset:32352
	v_pk_add_f32 v[250:251], v[250:251], v[184:185]
	v_pk_add_f32 v[250:251], v[250:251], v[186:187]
	v_pk_add_f32 v[250:251], v[250:251], v[188:189]
	s_waitcnt lgkmcnt(3)
	v_mfma_f32_32x32x16_f16 v[32:47], v[238:241], v[10:13], v[32:47]
	v_pk_add_f32 v[250:251], v[250:251], v[190:191]
	v_pk_add_f32 v[250:251], v[250:251], v[192:193]
	v_pk_add_f32 v[226:227], v[226:227], v[250:251]
	s_waitcnt lgkmcnt(2)
	v_mfma_f32_32x32x16_f16 v[16:31], v[242:245], v[10:13], v[16:31]
	v_add_f32_e32 v226, v226, v227
	v_add_f32_e32 v153, v153, v226
	s_waitcnt lgkmcnt(1)
	v_mfma_f32_32x32x16_f16 v[32:47], v[194:197], v[246:249], v[32:47]
	s_waitcnt lgkmcnt(0)
	v_mfma_f32_32x32x16_f16 v[16:31], v[198:201], v[246:249], v[16:31]
	s_branch .LBB0_2743
; #define MFMA(a, b, c) __builtin_amdgcn_mfma_f32_32x32x16_f16((a), (b), (c), 0, 0, 0)
; template <int DK, bool MLA>
; DI void attn_item(const h16* __restrict__ Q, const h16* __restrict__ Kp, const h16* __restrict__ Kr, const h16* __restrict__ Vt,
;                   int kbeg, int kend, h16* __restrict__ out, h16* sm) {
;     ...
;     float ps = 0.f;
; #pragma unroll
;     for (int i = 0; i < 16; ++i) {
;       st[0][i] = __builtin_amdgcn_exp2f(st[0][i]);
;       st[1][i] = __builtin_amdgcn_exp2f(st[1][i]);
;       ps += st[0][i] + st[1][i];
;     }
;     lsum += ps;
; #pragma unroll
;     for (int s4 = 0; s4 < 4; ++s4) {
;       const int kt2 = s4 >> 1, hf = s4 & 1;
;       h16x8 pb;
; #pragma unroll
;       for (int j = 0; j < 8; ++j) pb[j] = (h16)st[kt2][8 * hf + j];
;       const int kb = kt2 * 32 + 16 * hf;
; #pragma unroll
;       for (int dt = 0; dt < 2; ++dt) {
;         const h16* vp = vsm + (dt * 32 + r) * 72 + kb + 4 * hh;
;         h16x4 lo = *(const h16x4*)vp, hi = *(const h16x4*)(vp + 8);
;         h16x8 va = __builtin_shufflevector(lo, hi, 0, 1, 2, 3, 4, 5, 6, 7);
;         ot[dt] = MFMA(va, pb, ot[dt]);
;       }
;     }
.Lgq_drain2:
	ds_read_b128 v[238:241], v143 offset:46080
	ds_read_b128 v[242:245], v143 offset:50688
	ds_read_b128 v[194:197], v143 offset:46112
	ds_read_b128 v[198:201], v143 offset:50720
	v_exp_f32_e32 v162, v162
	v_exp_f32_e32 v163, v163
	v_exp_f32_e32 v164, v164
	v_exp_f32_e32 v165, v165
	v_exp_f32_e32 v166, v166
	v_exp_f32_e32 v167, v167
	v_exp_f32_e32 v168, v168
	v_exp_f32_e32 v169, v169
	v_cvt_pk_f16_f32 v2, v162, v163
	v_cvt_pk_f16_f32 v3, v164, v165
	v_exp_f32_e32 v170, v170
	v_exp_f32_e32 v171, v171
	v_exp_f32_e32 v172, v172
	v_exp_f32_e32 v173, v173
	v_cvt_pk_f16_f32 v4, v166, v167
	v_cvt_pk_f16_f32 v5, v168, v169
	v_exp_f32_e32 v174, v174
	v_exp_f32_e32 v175, v175
	v_exp_f32_e32 v176, v176
	v_exp_f32_e32 v177, v177
	v_cvt_pk_f16_f32 v6, v170, v171
	v_cvt_pk_f16_f32 v7, v172, v173
	v_exp_f32_e32 v178, v178
	v_exp_f32_e32 v179, v179
	v_exp_f32_e32 v180, v180
	v_exp_f32_e32 v181, v181
	v_cvt_pk_f16_f32 v8, v174, v175
	v_cvt_pk_f16_f32 v9, v176, v177
	v_exp_f32_e32 v182, v182
	v_exp_f32_e32 v183, v183
	v_exp_f32_e32 v184, v184
	v_exp_f32_e32 v185, v185
	v_cvt_pk_f16_f32 v10, v178, v179
	v_cvt_pk_f16_f32 v11, v180, v181
	v_exp_f32_e32 v186, v186
	v_exp_f32_e32 v187, v187
	v_exp_f32_e32 v188, v188
	v_exp_f32_e32 v189, v189
	v_cvt_pk_f16_f32 v12, v182, v183
	v_cvt_pk_f16_f32 v13, v184, v185
	v_exp_f32_e32 v190, v190
	v_exp_f32_e32 v191, v191
	v_exp_f32_e32 v192, v192
	v_exp_f32_e32 v193, v193
	v_cvt_pk_f16_f32 v246, v186, v187
	v_cvt_pk_f16_f32 v247, v188, v189
	v_cvt_pk_f16_f32 v248, v190, v191
	v_cvt_pk_f16_f32 v249, v192, v193
	s_nop 1
	s_waitcnt lgkmcnt(3)
	v_mfma_f32_32x32x16_f16 v[32:47], v[238:241], v[2:5], v[32:47]
	ds_read_b128 v[238:241], v143 offset:46144
	v_pk_add_f32 v[226:227], v[162:163], v[164:165]
	v_pk_add_f32 v[226:227], v[226:227], v[166:167]
	v_pk_add_f32 v[226:227], v[226:227], v[168:169]
	s_waitcnt lgkmcnt(3)
	v_mfma_f32_32x32x16_f16 v[16:31], v[242:245], v[2:5], v[16:31]
	ds_read_b128 v[242:245], v143 offset:50752
	v_pk_add_f32 v[226:227], v[226:227], v[170:171]
	v_pk_add_f32 v[226:227], v[226:227], v[172:173]
	v_pk_add_f32 v[226:227], v[226:227], v[174:175]
	s_waitcnt lgkmcnt(3)
	v_mfma_f32_32x32x16_f16 v[32:47], v[194:197], v[6:9], v[32:47]
	ds_read_b128 v[194:197], v143 offset:46176
	v_pk_add_f32 v[226:227], v[226:227], v[176:177]
	v_pk_add_f32 v[250:251], v[178:179], v[180:181]
	v_pk_add_f32 v[250:251], v[250:251], v[182:183]
	s_waitcnt lgkmcnt(3)
	v_mfma_f32_32x32x16_f16 v[16:31], v[198:201], v[6:9], v[16:31]
	ds_read_b128 v[198:201], v143 offset:50784
	v_pk_add_f32 v[250:251], v[250:251], v[184:185]
	v_pk_add_f32 v[250:251], v[250:251], v[186:187]
	v_pk_add_f32 v[250:251], v[250:251], v[188:189]
	s_waitcnt lgkmcnt(3)
	v_mfma_f32_32x32x16_f16 v[32:47], v[238:241], v[10:13], v[32:47]
	v_pk_add_f32 v[250:251], v[250:251], v[190:191]
	v_pk_add_f32 v[250:251], v[250:251], v[192:193]
	v_pk_add_f32 v[226:227], v[226:227], v[250:251]
	s_waitcnt lgkmcnt(2)
	v_mfma_f32_32x32x16_f16 v[16:31], v[242:245], v[10:13], v[16:31]
	v_add_f32_e32 v226, v226, v227
	v_add_f32_e32 v153, v153, v226
	s_waitcnt lgkmcnt(1)
	v_mfma_f32_32x32x16_f16 v[32:47], v[194:197], v[246:249], v[32:47]
	s_waitcnt lgkmcnt(0)
	v_mfma_f32_32x32x16_f16 v[16:31], v[198:201], v[246:249], v[16:31]
	s_branch .LBB0_2743
